# GEMM: one static s_setprio 1 for waves 4-7 for the whole GEMM phase, per-segment priority flips removed
# baseline (speedup 1.0000x reference)
.LBB0_793:
	s_andn2_b64 vcc, exec, s[2:3]
	s_cbranch_vccnz .LBB0_1112
	v_bfe_i32 v3, v0, 27, 1
	v_lshlrev_b32_e32 v4, 4, v0
	v_lshrrev_b32_e32 v3, 22, v3
	v_add_u32_e32 v3, v4, v3
	v_and_b32_e32 v3, 0xfffffc00, v3
	v_sub_u32_e32 v3, v4, v3
	v_lshrrev_b32_e32 v5, 4, v3
	v_ashrrev_i32_e32 v2, 31, v0
	v_bitop3_b32 v3, v5, v3, 32 bitop3:0x6c
	v_lshrrev_b32_e32 v2, 26, v2
	v_ashrrev_i32_e32 v6, 31, v3
	v_add_u32_e32 v2, v0, v2
	v_lshrrev_b32_e32 v6, 26, v6
	v_ashrrev_i32_e32 v2, 6, v2
	v_add_u32_e32 v6, v3, v6
	v_lshlrev_b32_e32 v5, 3, v2
	v_ashrrev_i32_e32 v7, 6, v6
	v_and_b32_e32 v6, 0xc0, v6
	v_and_b32_e32 v5, 0x7ffffff0, v5
	v_lshlrev_b32_e32 v2, 5, v2
	v_sub_u32_e32 v3, v3, v6
	v_add_u32_e32 v5, v7, v5
	v_and_b32_e32 v2, 32, v2
	v_ashrrev_i16_sdwa v3, v188, sext(v3) dst_sel:DWORD dst_unused:UNUSED_PAD src0_sel:DWORD src1_sel:BYTE_0
	v_bfe_i32 v6, v3, 0, 16
	v_mad_u64_u32 v[2:3], s[2:3], v5, s0, v[2:3]
	v_add_lshl_u32 v152, v2, v6, 1
	v_add_u32_e32 v2, 0x2000, v4
	v_ashrrev_i32_e32 v3, 31, v2
	v_lshrrev_b32_e32 v3, 22, v3
	v_add_u32_e32 v3, v2, v3
	v_ashrrev_i32_e32 v3, 10, v3
	v_mul_i32_i24_e32 v4, 0x400, v3
	v_sub_u32_e32 v2, v2, v4
	v_lshrrev_b32_e32 v4, 4, v2
	v_bitop3_b32 v4, v4, v2, 32 bitop3:0x6c
	v_ashrrev_i32_e32 v5, 31, v4
	v_lshrrev_b32_e32 v5, 26, v5
	v_lshlrev_b32_e32 v2, 3, v3
	v_add_u32_e32 v5, v4, v5
	v_and_b32_e32 v2, 0x7ffffff0, v2
	v_ashrrev_i32_e32 v6, 6, v5
	v_add_u32_e32 v6, v6, v2
	v_lshlrev_b32_e32 v2, 5, v3
	v_and_b32_e32 v3, 0xc0, v5
	v_sub_u32_e32 v3, v4, v3
	v_and_b32_e32 v2, 32, v2
	v_ashrrev_i16_sdwa v3, v188, sext(v3) dst_sel:DWORD dst_unused:UNUSED_PAD src0_sel:DWORD src1_sel:BYTE_0
	v_bfe_i32 v4, v3, 0, 16
	v_mad_u64_u32 v[2:3], s[2:3], v6, s0, v[2:3]
	s_lshl_b64 s[14:15], s[0:1], 9
	s_ashr_i32 s2, s66, 31
	s_lshl_b64 s[12:13], s[0:1], 8
	s_mul_i32 s2, s14, s2
	s_mul_hi_u32 s3, s14, s66
	s_lshr_b64 s[0:1], s[0:1], 23
	s_add_i32 s2, s3, s2
	s_mul_i32 s1, s0, s66
	s_add_i32 s1, s2, s1
	s_ashr_i32 s2, s65, 31
	s_mul_i32 s2, s14, s2
	s_mul_hi_u32 s3, s14, s65
	s_ashr_i32 s7, s6, 6
	s_ashr_i32 s27, s26, 31
	s_add_i32 s2, s3, s2
	s_mul_i32 s0, s0, s65
	s_ashr_i32 s43, s6, 8
	s_lshl_b32 s44, s7, 10
	s_lshl_b64 s[4:5], s[26:27], 7
	s_add_i32 s2, s2, s0
	s_mul_i32 s0, s14, s65
	s_add_u32 s0, s37, s0
	s_addc_u32 s3, s36, s2
	s_add_u32 s2, s0, s4
	s_addc_u32 s3, s3, s5
	s_add_i32 s27, s44, 0
	s_add_i32 m0, s27, 0x10000
	s_mul_i32 s8, s14, s66
	global_load_lds_dwordx4 v152, s[2:3]
	s_add_i32 m0, s27, 0x12000
	s_add_u32 s8, s35, s8
	s_addc_u32 s9, s34, s1
	v_add_lshl_u32 v154, v2, v4, 1
	s_add_u32 s0, s2, s12
	global_load_lds_dwordx4 v154, s[2:3]
	s_addc_u32 s1, s3, s13
	s_add_i32 m0, s27, 0x14000
	v_mov_b32_e32 v153, v1
	global_load_lds_dwordx4 v152, s[0:1]
	s_add_i32 m0, s27, 0x16000
	s_add_u32 s4, s8, s4
	s_addc_u32 s5, s9, s5
	s_add_i32 s45, s27, 0x2000
	global_load_lds_dwordx4 v154, s[0:1]
	s_mov_b32 m0, s27
	s_add_u32 s8, s4, s12
	global_load_lds_dwordx4 v152, s[4:5]
	s_mov_b32 m0, s45
	s_addc_u32 s9, s5, s13
	s_add_i32 s46, s27, 0x4000
	global_load_lds_dwordx4 v154, s[4:5]
	s_mov_b32 m0, s46
	s_add_i32 s47, s27, 0x6000
	global_load_lds_dwordx4 v152, s[8:9]
	s_mov_b32 m0, s47
	v_mov_b32_e32 v155, v1
	global_load_lds_dwordx4 v154, s[8:9]
	s_cmp_eq_u32 s43, 1
	s_waitcnt vmcnt(0)
	v_lshl_add_u64 v[12:13], s[2:3], 0, v[152:153]
	v_lshl_add_u64 v[10:11], s[2:3], 0, v[154:155]
	v_lshl_add_u64 v[4:5], s[0:1], 0, v[152:153]
	v_lshl_add_u64 v[2:3], s[0:1], 0, v[154:155]
	v_lshl_add_u64 v[6:7], s[4:5], 0, v[152:153]
	s_cselect_b64 s[16:17], -1, 0
	s_cmp_lg_u32 s43, 1
	v_lshl_add_u64 v[8:9], s[4:5], 0, v[154:155]
	s_cbranch_scc1 .LBB0_796
	s_setprio 1
	s_barrier

.LBB0_1111:
	s_setprio 0
	s_waitcnt vmcnt(0)
	v_readlane_b32 s18, v253, 51
	v_readlane_b32 s48, v253, 49
	s_movk_i32 s49, 0x3fff
	s_mov_b32 s50, 0x800000
	s_movk_i32 s51, 0x40ff
	s_mov_b32 s52, 0x2aaaaaab
	s_movk_i32 s53, 0x80
	s_movk_i32 s54, 0x7ff
	s_movk_i32 s55, 0xfff
	s_movk_i32 s56, 0x3ff
	s_movk_i32 s57, 0xfa00
	s_movk_i32 s58, 0x1800
	s_movk_i32 s59, 0x500
	s_movk_i32 s60, 0xff00
	s_movk_i32 s61, 0x2ff
	s_movk_i32 s62, 0x1ff
	s_movk_i32 s63, 0x67
	s_movk_i32 s64, 0x6f
	s_movk_i32 s27, 0x77
	s_movk_i32 s29, 0x7f
	v_readlane_b32 s30, v253, 50
	s_mov_b32 s31, 0x3f2aaaab
	s_mov_b32 s43, 0x3f317218
	s_mov_b32 s44, 0x7f800000
	s_mov_b32 s45, 0x33800000
	s_movk_i32 s47, 0x210
	s_movk_i32 s46, 0x1000
	v_readlane_b32 s19, v253, 52
	s_barrier
